# block-0 P.V MFMAs interleaved into the score chain; K and V block-0 fragment reads requested alternately; block-1 V reads in the score gaps
# speedup vs baseline: 1.0045x; 1.0030x over previous
; #define SBAR() __builtin_amdgcn_sched_barrier(0)
; #define KDMA(k0, b) do { const char* g_ = (const char*)(Kh + (long)(k0) * DM); char* l_ = K_lds + (b) * 16384 + wu * 1024; \
;     DMA16(g_ + koff[0], l_); DMA16(g_ + koff[1], l_ + 8192); } while (0)
; #define VDMA(k0, b) do { const char* g_ = (const char*)(Vh + (long)(k0) * DM); char* l_ = V_lds + (b) * 32768 + wu * 1024; \
;     DMA16(g_ + voff[0], l_); DMA16(g_ + voff[1], l_ + 8192); DMA16(g_ + voff[0] + 256, l_ + 16384); DMA16(g_ + voff[1] + 256, l_ + 16384 + 8192); } while (0)
; #define VRD(D0, X) do { X##0 = tr_read<v_rd_off(D0, 0, 0)>(vb); X##1 = tr_read<v_rd_off(D0, 0, 1)>(vb); X##2 = tr_read<v_rd_off(D0, 1, 0)>(vb); X##3 = tr_read<v_rd_off(D0, 1, 1)>(vb); \
;     X##4 = tr_read<v_rd_off(D0, 2, 0)>(vb); X##5 = tr_read<v_rd_off(D0, 2, 1)>(vb); X##6 = tr_read<v_rd_off(D0, 3, 0)>(vb); X##7 = tr_read<v_rd_off(D0, 3, 1)>(vb); } while (0)
; template <int PROBE, int MODE>
; DI void dattn_body(const u16* __restrict__ Qb, const u16* __restrict__ Kh, const u16* __restrict__ Vh, u16* __restrict__ Ob, const u16* __restrict__ O1, float lam, const float* __restrict__ subg, int seq, int q0, float kmax2, char* lds) {
;     ...
;   for (int j = 0; j < NT; ++j) {
;     const bool more = j + 1 < NT;
;     if (!(PROBE & 1)) {
;       if (j + 2 < NT) KDMA((j + 2) * KVBLK, j & 1);
;       if (more) VDMA((j + 1) * KVBLK, (j + 1) & 1);
;     }
;     bf16x8 kf[8];
;     if (more) { const char* Ks_ = K_lds + ((j + 1) & 1) * 16384;
; #pragma unroll
;       for (int d0 = 0; d0 < 8; ++d0) kf[d0] = *reinterpret_cast<const bf16x8*>(Ks_ + KSWZ(32 * kh + r32, (d0 * 16 + hi * 8) * 2)); }
;     const bf16x8 pb0 = *(const bf16x8*)(pr + (j & 1) * 16384), pb1 = *(const bf16x8*)(pr + (j & 1) * 16384 + 16);
;     const int vb = vb0 + (j & 1) * 32768;
;     s16x4 va0, va1, va2, va3, va4, va5, va6, va7, vc0, vc1, vc2, vc3, vc4, vc5, vc6, vc7;
;     VRD(0, va);
;     if (more) { asm volatile("s_waitcnt lgkmcnt(10)" ::: "memory"); SBAR();
;       if (!(PROBE & 4)) { S = f32x16{};
; #pragma unroll
;       for (int d0 = 0; d0 < 8; ++d0) S = __builtin_amdgcn_mfma_f32_32x32x16_bf16(kf[d0], qr[d0], S, 0, 0, 0); }
;       SBAR(); }
;     const bf16x8 A0 = kh ? pb0 : po0, A1 = kh ? pb1 : po1, A2 = kh ? po0 : pb0, A3 = kh ? po1 : pb1;
;     SMX_SETUP(j + 1)
;     ...
;     LWAIT(); VRD(1, vc); VMMP(0, va); SMXP(0);
;     LWAIT(); VRD(2, va); VMMP(1, vc); SMXP(1);
.Lfast0:
	s_sub_i32 s72, s18, 64
	s_and_b32 s101, s25, 0x4000
	s_addk_i32 s25, 0x4000
	s_and_b32 s19, s25, 0x4000
	s_and_b32 s48, s55, 1
	v_lshl_add_u32 v68, s48, 14, v210
	ds_read_b128 v[162:165], v68
	ds_read_b128 v[166:169], v68 offset:16
	s_bfe_u32 s100, s85, 0x1000a
	s_lshl_b32 s100, s100, 13
	s_lshl_b32 s48, s48, 15
	s_sub_i32 s74, s48, s100
	s_add_i32 s48, s48, s100
	v_add_u32_e32 v216, s48, v212
	v_add_u32_e32 v233, s74, v212
	v_add_u32_e32 v68, s19, v213
	v_add_u32_e32 v64, v68, v198
	v_add_u32_e32 v69, v68, v199
	ds_read_b128 v[64:67], v64
	ds_read_b128 v[118:121], v69
	ds_read_b64_tr_b16 v[234:235], v216 offset:0
	ds_read_b64_tr_b16 v[236:237], v216 offset:0x800
	v_add_u32_e32 v69, v68, v200
	v_add_u32_e32 v70, v68, v201
	ds_read_b128 v[122:125], v69
	ds_read_b128 v[126:129], v70
	ds_read_b64_tr_b16 v[238:239], v216 offset:0x1000
	ds_read_b64_tr_b16 v[240:241], v216 offset:0x1800
	v_add_u32_e32 v69, v68, v202
	v_add_u32_e32 v70, v68, v203
	ds_read_b128 v[134:137], v69
	ds_read_b128 v[138:141], v70
	v_add_u32_e32 v142, v68, v204
	v_add_u32_e32 v146, v68, v205
	s_cmp_gt_i32 s72, s87
	s_cselect_b32 s100, s21, s20
	v_sub_f32_e32 v160, s100, v158
	s_lshl_b32 s48, s72, 12
	s_add_u32 s48, s16, s48
	s_addc_u32 s49, s17, 0
	s_add_u32 s74, s48, 0x100
	s_addc_u32 s75, s49, 0
	s_and_b32 s100, s54, 0x8000
	s_add_i32 s100, s85, s100
	s_waitcnt lgkmcnt(9)
	v_mfma_f32_32x32x16_bf16 v[64:79], v[64:67], v[82:85], 0
	ds_read_b64_tr_b16 v[242:243], v233 offset:0x2000
	ds_read_b64_tr_b16 v[244:245], v233 offset:0x2800
	s_waitcnt lgkmcnt(10)
	v_mfma_f32_32x32x16_bf16 v[64:79], v[118:121], v[86:89], v[64:79]
	ds_read_b128 v[142:145], v142
	ds_read_b128 v[146:149], v146
	s_waitcnt lgkmcnt(10)
	v_mfma_f32_32x32x16_bf16 v[0:15], v[114:117], v[234:237], v[0:15]
	ds_read_b64_tr_b16 v[246:247], v233 offset:0x3000
	ds_read_b64_tr_b16 v[248:249], v233 offset:0x3800
	s_waitcnt lgkmcnt(11)
	v_mfma_f32_32x32x16_bf16 v[64:79], v[122:125], v[90:93], v[64:79]
	s_waitcnt lgkmcnt(10)
	v_mfma_f32_32x32x16_bf16 v[64:79], v[126:129], v[94:97], v[64:79]
	ds_read_b64_tr_b16 v[126:127], v233 offset:0x3200
	ds_read_b64_tr_b16 v[128:129], v233 offset:0x3a00
	s_waitcnt lgkmcnt(10)
	v_mfma_f32_32x32x16_bf16 v[0:15], v[130:133], v[238:241], v[0:15]
	s_mov_b32 m0, s100
	s_waitcnt lgkmcnt(9)
	v_mfma_f32_32x32x16_bf16 v[64:79], v[134:137], v[98:101], v[64:79]
	global_load_lds_dwordx4 v176, s[48:49]
	ds_read_b64_tr_b16 v[134:135], v233 offset:0x2200
	ds_read_b64_tr_b16 v[136:137], v233 offset:0x2a00
	s_add_i32 m0, s100, 0x2000
	s_waitcnt lgkmcnt(10)
	v_mfma_f32_32x32x16_bf16 v[64:79], v[138:141], v[102:105], v[64:79]
	global_load_lds_dwordx4 v156, s[48:49]
	ds_read_b64_tr_b16 v[138:139], v216 offset:0x200
	ds_read_b64_tr_b16 v[140:141], v216 offset:0xa00
	s_add_i32 m0, s100, 0x4000
	s_waitcnt lgkmcnt(10)
	v_mfma_f32_32x32x16_bf16 v[0:15], v[162:165], v[242:245], v[0:15]
	global_load_lds_dwordx4 v176, s[74:75]
	s_add_i32 m0, s100, 0x6000
	s_waitcnt lgkmcnt(9)
	v_mfma_f32_32x32x16_bf16 v[64:79], v[142:145], v[106:109], v[64:79]
	ds_read_b64_tr_b16 v[142:143], v216 offset:0x1200
	ds_read_b64_tr_b16 v[144:145], v216 offset:0x1a00
	s_waitcnt lgkmcnt(10)
	v_mfma_f32_32x32x16_bf16 v[64:79], v[146:149], v[110:113], v[64:79]
	global_load_lds_dwordx4 v156, s[74:75]
	s_waitcnt lgkmcnt(8)
	v_mfma_f32_32x32x16_bf16 v[0:15], v[166:169], v[246:249], v[0:15]
	s_add_i32 s48, s55, 2
	s_cmp_ge_u32 s48, s11
	s_cbranch_scc1 .Lfast0_k_done
	s_lshl_b32 s48, s18, 12
	s_add_u32 s48, s14, s48
	s_addc_u32 s49, s15, 0
	s_add_i32 s100, s82, s101
	s_mov_b32 m0, s100
	s_nop 0
	global_load_lds_dwordx4 v152, s[48:49]
	s_add_i32 m0, s100, 0x2000
	s_nop 0
	global_load_lds_dwordx4 v154, s[48:49]
; #define DMAWAIT() asm volatile("s_waitcnt vmcnt(0)" ::: "memory")
; #define SMX_FIN(pbuf) do { _Pragma("unroll") for (int r = 0; r < 16; ++r) l_reg += S[r]; \
;     PK4S(0, po0); PK4S(8, po1); \
;     *(bf16x8*)(pw + (pbuf) * 16384) = po0; *(bf16x8*)(pw + (pbuf) * 16384 + 16) = po1; } while (0)
; #define VRD(D0, X) do { X##0 = tr_read<v_rd_off(D0, 0, 0)>(vb); X##1 = tr_read<v_rd_off(D0, 0, 1)>(vb); X##2 = tr_read<v_rd_off(D0, 1, 0)>(vb); X##3 = tr_read<v_rd_off(D0, 1, 1)>(vb); \
;     X##4 = tr_read<v_rd_off(D0, 2, 0)>(vb); X##5 = tr_read<v_rd_off(D0, 2, 1)>(vb); X##6 = tr_read<v_rd_off(D0, 3, 0)>(vb); X##7 = tr_read<v_rd_off(D0, 3, 1)>(vb); } while (0)
; #define LWAIT() do { asm volatile("s_waitcnt lgkmcnt(0)" ::: "memory"); SBAR(); } while (0)
; #define VMMP(D0, X) do { if (!(PROBE & 8)) VMM(D0, X); } while (0)
; #define SMXP(c) do { if (!(PROBE & 2)) { if (more) SMX_CH(c); } } while (0)
; template <int PROBE, int MODE>
; DI void dattn_body(const u16* __restrict__ Qb, const u16* __restrict__ Kh, const u16* __restrict__ Vh, u16* __restrict__ Ob, const u16* __restrict__ O1, float lam, const float* __restrict__ subg, int seq, int q0, float kmax2, char* lds) {
;     ...
;     LWAIT(); VRD(1, vc); VMMP(0, va); SMXP(0);
;     LWAIT(); VRD(2, va); VMMP(1, vc); SMXP(1);
;     LWAIT(); VRD(3, vc); VMMP(2, va); SMXP(2);
;     LWAIT(); VMMP(3, vc); SMXP(3);
;     if (!(PROBE & 2)) { if (more) SMX_FIN((j + 1) & 1); }
;     DMAWAIT();
;     __syncthreads();
.Lfast0_k_done:
	s_waitcnt lgkmcnt(2)
	v_mfma_f32_32x32x16_bf16 v[16:31], v[114:117], v[138:141], v[16:31]
	ds_read_b64_tr_b16 v[146:147], v216 offset:0x400
	ds_read_b64_tr_b16 v[148:149], v216 offset:0xc00
	s_nop 4
	v_fma_f32 v118, v64, s12, v160
	v_fma_f32 v119, v65, s12, v160
	v_fma_f32 v120, v66, s12, v160
	v_fma_f32 v121, v67, s12, v160
	v_fma_f32 v122, v68, s12, v160
	v_fma_f32 v123, v69, s12, v160
	s_waitcnt lgkmcnt(2)
	v_mfma_f32_32x32x16_bf16 v[16:31], v[130:133], v[142:145], v[16:31]
	ds_read_b64_tr_b16 v[142:143], v216 offset:0x1400
	ds_read_b64_tr_b16 v[144:145], v216 offset:0x1c00
	v_fma_f32 v124, v70, s12, v160
	v_fma_f32 v125, v71, s12, v160
	v_exp_f32_e32 v118, v118
	v_exp_f32_e32 v119, v119
	v_exp_f32_e32 v120, v120
	v_exp_f32_e32 v121, v121
	v_fma_f32 v244, v72, s12, v160
	v_fma_f32 v245, v73, s12, v160
	v_mfma_f32_32x32x16_bf16 v[16:31], v[162:165], v[134:137], v[16:31]
	ds_read_b64_tr_b16 v[138:139], v233 offset:0x2400
	ds_read_b64_tr_b16 v[140:141], v233 offset:0x2c00
	v_exp_f32_e32 v122, v122
	v_exp_f32_e32 v123, v123
	v_add_f32_e32 v209, v118, v209
	v_add_f32_e32 v209, v119, v209
	v_fma_f32 v246, v74, s12, v160
	v_fma_f32 v247, v75, s12, v160
	v_fma_f32 v76, v76, s12, v160
	v_fma_f32 v77, v77, s12, v160
	v_mfma_f32_32x32x16_bf16 v[16:31], v[166:169], v[126:129], v[16:31]
	ds_read_b64_tr_b16 v[64:65], v233 offset:0x3400
	ds_read_b64_tr_b16 v[66:67], v233 offset:0x3c00
	v_exp_f32_e32 v124, v124
	v_exp_f32_e32 v125, v125
	v_add_f32_e32 v209, v120, v209
	v_add_f32_e32 v209, v121, v209
	v_add_f32_e32 v209, v122, v209
	v_add_f32_e32 v209, v123, v209
	v_fma_f32 v78, v78, s12, v160
	v_fma_f32 v79, v79, s12, v160
	s_waitcnt lgkmcnt(6)
	v_mfma_f32_32x32x16_bf16 v[32:47], v[114:117], v[146:149], v[32:47]
	v_exp_f32_e32 v244, v244
	v_exp_f32_e32 v245, v245
	v_add_f32_e32 v209, v124, v209
	v_add_f32_e32 v209, v125, v209
	s_waitcnt lgkmcnt(4)
	v_mfma_f32_32x32x16_bf16 v[32:47], v[130:133], v[142:145], v[32:47]
	ds_read_b64_tr_b16 v[142:143], v216 offset:0x600
	ds_read_b64_tr_b16 v[144:145], v216 offset:0xe00
	ds_read_b64_tr_b16 v[126:127], v216 offset:0x1600
	ds_read_b64_tr_b16 v[128:129], v216 offset:0x1e00
	v_exp_f32_e32 v246, v246
	v_exp_f32_e32 v247, v247
	s_waitcnt lgkmcnt(6)
	v_mfma_f32_32x32x16_bf16 v[32:47], v[162:165], v[138:141], v[32:47]
	ds_read_b64_tr_b16 v[134:135], v233 offset:0x2600
	ds_read_b64_tr_b16 v[136:137], v233 offset:0x2e00
	v_exp_f32_e32 v76, v76
	v_exp_f32_e32 v77, v77
	v_add_f32_e32 v209, v244, v209
	v_add_f32_e32 v209, v245, v209
	s_waitcnt lgkmcnt(6)
	v_mfma_f32_32x32x16_bf16 v[32:47], v[166:169], v[64:67], v[32:47]
	ds_read_b64_tr_b16 v[68:69], v233 offset:0x3600
	ds_read_b64_tr_b16 v[70:71], v233 offset:0x3e00
	v_exp_f32_e32 v78, v78
	v_exp_f32_e32 v79, v79
	v_add_f32_e32 v209, v246, v209
	v_add_f32_e32 v209, v247, v209
	s_waitcnt lgkmcnt(6)
	v_mfma_f32_32x32x16_bf16 v[48:63], v[114:117], v[142:145], v[48:63]
	v_add_u32_e32 v64, s19, v211
	v_add_f32_e32 v209, v76, v209
	v_add_f32_e32 v209, v77, v209
	v_cvt_pk_bf16_f32 v114, v118, v119
	v_cvt_pk_bf16_f32 v115, v120, v121
	v_cvt_pk_bf16_f32 v116, v122, v123
	v_cvt_pk_bf16_f32 v117, v124, v125
	s_waitcnt lgkmcnt(4)
	v_mfma_f32_32x32x16_bf16 v[48:63], v[130:133], v[126:129], v[48:63]
	v_add_f32_e32 v209, v78, v209
	v_add_f32_e32 v209, v79, v209
	v_permlane32_swap_b32_e32 v114, v116
	v_permlane32_swap_b32_e32 v115, v117
	v_cvt_pk_bf16_f32 v130, v244, v245
	v_cvt_pk_bf16_f32 v131, v246, v247
	v_cvt_pk_bf16_f32 v132, v76, v77
	v_cvt_pk_bf16_f32 v133, v78, v79
	ds_write_b128 v64, v[114:117]
	s_waitcnt lgkmcnt(3)
	v_mfma_f32_32x32x16_bf16 v[48:63], v[162:165], v[134:137], v[48:63]
	v_permlane32_swap_b32_e32 v130, v132
	v_permlane32_swap_b32_e32 v131, v133
	ds_write_b128 v64, v[130:133] offset:16
	s_add_i32 s55, s55, 1
	s_add_i32 s18, s18, 64
	s_add_i32 s54, s54, 0x8000
	s_add_i32 s100, s18, -1
	s_cmp_ge_i32 s100, s33
	s_cselect_b32 s100, 1, 0
	s_sub_i32 s101, s18, 64
	s_cmp_le_i32 s101, s35
	s_cselect_b32 s101, 1, 0
	s_and_b32 s100, s100, s101
	s_cmp_eq_u32 s83, s55
	s_waitcnt vmcnt(0) lgkmcnt(0)
	s_barrier
	v_mfma_f32_32x32x16_bf16 v[48:63], v[166:169], v[68:71], v[48:63]
	s_cbranch_scc1 .LBB0_265
	s_cmp_lg_u32 s100, 0
	s_cbranch_scc1 .Lgen0
	s_branch .Lfast0

; #define SBAR() __builtin_amdgcn_sched_barrier(0)
; #define KDMA(k0, b) do { const char* g_ = (const char*)(Kh + (long)(k0) * DM); char* l_ = K_lds + (b) * 16384 + wu * 1024; \
;     DMA16(g_ + koff[0], l_); DMA16(g_ + koff[1], l_ + 8192); } while (0)
; #define VDMA(k0, b) do { const char* g_ = (const char*)(Vh + (long)(k0) * DM); char* l_ = V_lds + (b) * 32768 + wu * 1024; \
;     DMA16(g_ + voff[0], l_); DMA16(g_ + voff[1], l_ + 8192); DMA16(g_ + voff[0] + 256, l_ + 16384); DMA16(g_ + voff[1] + 256, l_ + 16384 + 8192); } while (0)
; #define VRD(D0, X) do { X##0 = tr_read<v_rd_off(D0, 0, 0)>(vb); X##1 = tr_read<v_rd_off(D0, 0, 1)>(vb); X##2 = tr_read<v_rd_off(D0, 1, 0)>(vb); X##3 = tr_read<v_rd_off(D0, 1, 1)>(vb); \
;     X##4 = tr_read<v_rd_off(D0, 2, 0)>(vb); X##5 = tr_read<v_rd_off(D0, 2, 1)>(vb); X##6 = tr_read<v_rd_off(D0, 3, 0)>(vb); X##7 = tr_read<v_rd_off(D0, 3, 1)>(vb); } while (0)
; template <int PROBE, int MODE>
; DI void dattn_body(const u16* __restrict__ Qb, const u16* __restrict__ Kh, const u16* __restrict__ Vh, u16* __restrict__ Ob, const u16* __restrict__ O1, float lam, const float* __restrict__ subg, int seq, int q0, float kmax2, char* lds) {
;     ...
;   for (int j = 0; j < NT; ++j) {
;     const bool more = j + 1 < NT;
;     if (!(PROBE & 1)) {
;       if (j + 2 < NT) KDMA((j + 2) * KVBLK, j & 1);
;       if (more) VDMA((j + 1) * KVBLK, (j + 1) & 1);
;     }
;     bf16x8 kf[8];
;     if (more) { const char* Ks_ = K_lds + ((j + 1) & 1) * 16384;
; #pragma unroll
;       for (int d0 = 0; d0 < 8; ++d0) kf[d0] = *reinterpret_cast<const bf16x8*>(Ks_ + KSWZ(32 * kh + r32, (d0 * 16 + hi * 8) * 2)); }
;     const bf16x8 pb0 = *(const bf16x8*)(pr + (j & 1) * 16384), pb1 = *(const bf16x8*)(pr + (j & 1) * 16384 + 16);
;     const int vb = vb0 + (j & 1) * 32768;
;     s16x4 va0, va1, va2, va3, va4, va5, va6, va7, vc0, vc1, vc2, vc3, vc4, vc5, vc6, vc7;
;     VRD(0, va);
;     if (more) { asm volatile("s_waitcnt lgkmcnt(10)" ::: "memory"); SBAR();
;       if (!(PROBE & 4)) { S = f32x16{};
; #pragma unroll
;       for (int d0 = 0; d0 < 8; ++d0) S = __builtin_amdgcn_mfma_f32_32x32x16_bf16(kf[d0], qr[d0], S, 0, 0, 0); }
;       SBAR(); }
;     const bf16x8 A0 = kh ? pb0 : po0, A1 = kh ? pb1 : po1, A2 = kh ? po0 : pb0, A3 = kh ? po1 : pb1;
;     SMX_SETUP(j + 1)
;     ...
;     LWAIT(); VRD(1, vc); VMMP(0, va); SMXP(0);
;     LWAIT(); VRD(2, va); VMMP(1, vc); SMXP(1);
.Lfast1:
	s_sub_i32 s72, s0, 64
	s_and_b32 s101, s24, 0x4000
	s_addk_i32 s24, 0x4000
	s_and_b32 s1, s24, 0x4000
	s_and_b32 s4, s40, 1
	v_lshl_add_u32 v68, s4, 14, v209
	ds_read_b128 v[162:165], v68
	ds_read_b128 v[166:169], v68 offset:16
	s_bfe_u32 s100, s39, 0x1000a
	s_lshl_b32 s100, s100, 13
	s_lshl_b32 s4, s4, 15
	s_sub_i32 s18, s4, s100
	s_add_i32 s4, s4, s100
	v_add_u32_e32 v215, s4, v211
	v_add_u32_e32 v233, s18, v211
	v_add_u32_e32 v68, s1, v212
	v_add_u32_e32 v64, v68, v196
	v_add_u32_e32 v69, v68, v198
	ds_read_b128 v[64:67], v64
	ds_read_b128 v[118:121], v69
	ds_read_b64_tr_b16 v[234:235], v215 offset:0
	ds_read_b64_tr_b16 v[236:237], v215 offset:0x800
	v_add_u32_e32 v69, v68, v199
	v_add_u32_e32 v70, v68, v200
	ds_read_b128 v[122:125], v69
	ds_read_b128 v[126:129], v70
	ds_read_b64_tr_b16 v[238:239], v215 offset:0x1000
	ds_read_b64_tr_b16 v[240:241], v215 offset:0x1800
	v_add_u32_e32 v69, v68, v201
	v_add_u32_e32 v70, v68, v202
	ds_read_b128 v[134:137], v69
	ds_read_b128 v[138:141], v70
	v_add_u32_e32 v142, v68, v203
	v_add_u32_e32 v146, v68, v204
	s_cmp_gt_i32 s72, s87
	s_cselect_b32 s100, s21, s20
	v_sub_f32_e32 v160, s100, v158
	s_lshl_b32 s4, s72, 12
	s_add_u32 s4, s16, s4
	s_addc_u32 s5, s17, 0
	s_add_u32 s18, s4, 0x100
	s_addc_u32 s19, s5, 0
	s_and_b32 s100, s25, 0x8000
	s_add_i32 s100, s39, s100
	s_waitcnt lgkmcnt(9)
	v_mfma_f32_32x32x16_bf16 v[64:79], v[64:67], v[82:85], 0
	ds_read_b64_tr_b16 v[242:243], v233 offset:0x2000
	ds_read_b64_tr_b16 v[244:245], v233 offset:0x2800
	s_waitcnt lgkmcnt(10)
	v_mfma_f32_32x32x16_bf16 v[64:79], v[118:121], v[86:89], v[64:79]
	ds_read_b128 v[142:145], v142
	ds_read_b128 v[146:149], v146
	s_waitcnt lgkmcnt(10)
	v_mfma_f32_32x32x16_bf16 v[0:15], v[114:117], v[234:237], v[0:15]
	ds_read_b64_tr_b16 v[246:247], v233 offset:0x3000
	ds_read_b64_tr_b16 v[248:249], v233 offset:0x3800
	s_waitcnt lgkmcnt(11)
	v_mfma_f32_32x32x16_bf16 v[64:79], v[122:125], v[90:93], v[64:79]
	s_waitcnt lgkmcnt(10)
	v_mfma_f32_32x32x16_bf16 v[64:79], v[126:129], v[94:97], v[64:79]
	ds_read_b64_tr_b16 v[126:127], v233 offset:0x3200
	ds_read_b64_tr_b16 v[128:129], v233 offset:0x3a00
	s_waitcnt lgkmcnt(10)
	v_mfma_f32_32x32x16_bf16 v[0:15], v[130:133], v[238:241], v[0:15]
	s_mov_b32 m0, s100
	s_waitcnt lgkmcnt(9)
	v_mfma_f32_32x32x16_bf16 v[64:79], v[134:137], v[98:101], v[64:79]
	global_load_lds_dwordx4 v152, s[4:5]
	ds_read_b64_tr_b16 v[134:135], v233 offset:0x2200
	ds_read_b64_tr_b16 v[136:137], v233 offset:0x2a00
	s_add_i32 m0, s100, 0x2000
	s_waitcnt lgkmcnt(10)
	v_mfma_f32_32x32x16_bf16 v[64:79], v[138:141], v[102:105], v[64:79]
	global_load_lds_dwordx4 v156, s[4:5]
	ds_read_b64_tr_b16 v[138:139], v215 offset:0x200
	ds_read_b64_tr_b16 v[140:141], v215 offset:0xa00
	s_add_i32 m0, s100, 0x4000
	s_waitcnt lgkmcnt(10)
	v_mfma_f32_32x32x16_bf16 v[0:15], v[162:165], v[242:245], v[0:15]
	global_load_lds_dwordx4 v152, s[18:19]
	s_add_i32 m0, s100, 0x6000
	s_waitcnt lgkmcnt(9)
	v_mfma_f32_32x32x16_bf16 v[64:79], v[142:145], v[106:109], v[64:79]
	ds_read_b64_tr_b16 v[142:143], v215 offset:0x1200
	ds_read_b64_tr_b16 v[144:145], v215 offset:0x1a00
	s_waitcnt lgkmcnt(10)
	v_mfma_f32_32x32x16_bf16 v[64:79], v[146:149], v[110:113], v[64:79]
	global_load_lds_dwordx4 v156, s[18:19]
	s_waitcnt lgkmcnt(8)
	v_mfma_f32_32x32x16_bf16 v[0:15], v[166:169], v[246:249], v[0:15]
	s_add_i32 s4, s40, 2
	s_cmp_ge_u32 s4, s11
	s_cbranch_scc1 .Lfast1_k_done
	s_lshl_b32 s4, s0, 12
	s_add_u32 s4, s14, s4
	s_addc_u32 s5, s15, 0
	s_add_u32 s4, s4, 0x100
	s_addc_u32 s5, s5, 0
	s_add_i32 s100, s38, s101
	s_mov_b32 m0, s100
	s_nop 0
	global_load_lds_dwordx4 v176, s[4:5]
	s_add_i32 m0, s100, 0x2000
	s_nop 0
	global_load_lds_dwordx4 v154, s[4:5]
; #define DMAWAIT() asm volatile("s_waitcnt vmcnt(0)" ::: "memory")
; #define SMX_FIN(pbuf) do { _Pragma("unroll") for (int r = 0; r < 16; ++r) l_reg += S[r]; \
;     PK4S(0, po0); PK4S(8, po1); \
;     *(bf16x8*)(pw + (pbuf) * 16384) = po0; *(bf16x8*)(pw + (pbuf) * 16384 + 16) = po1; } while (0)
; #define VRD(D0, X) do { X##0 = tr_read<v_rd_off(D0, 0, 0)>(vb); X##1 = tr_read<v_rd_off(D0, 0, 1)>(vb); X##2 = tr_read<v_rd_off(D0, 1, 0)>(vb); X##3 = tr_read<v_rd_off(D0, 1, 1)>(vb); \
;     X##4 = tr_read<v_rd_off(D0, 2, 0)>(vb); X##5 = tr_read<v_rd_off(D0, 2, 1)>(vb); X##6 = tr_read<v_rd_off(D0, 3, 0)>(vb); X##7 = tr_read<v_rd_off(D0, 3, 1)>(vb); } while (0)
; #define LWAIT() do { asm volatile("s_waitcnt lgkmcnt(0)" ::: "memory"); SBAR(); } while (0)
; #define VMMP(D0, X) do { if (!(PROBE & 8)) VMM(D0, X); } while (0)
; #define SMXP(c) do { if (!(PROBE & 2)) { if (more) SMX_CH(c); } } while (0)
; template <int PROBE, int MODE>
; DI void dattn_body(const u16* __restrict__ Qb, const u16* __restrict__ Kh, const u16* __restrict__ Vh, u16* __restrict__ Ob, const u16* __restrict__ O1, float lam, const float* __restrict__ subg, int seq, int q0, float kmax2, char* lds) {
;     ...
;     LWAIT(); VRD(1, vc); VMMP(0, va); SMXP(0);
;     LWAIT(); VRD(2, va); VMMP(1, vc); SMXP(1);
;     LWAIT(); VRD(3, vc); VMMP(2, va); SMXP(2);
;     LWAIT(); VMMP(3, vc); SMXP(3);
;     if (!(PROBE & 2)) { if (more) SMX_FIN((j + 1) & 1); }
;     DMAWAIT();
;     __syncthreads();
.Lfast1_k_done:
	s_waitcnt lgkmcnt(2)
	v_mfma_f32_32x32x16_bf16 v[16:31], v[114:117], v[138:141], v[16:31]
	ds_read_b64_tr_b16 v[146:147], v215 offset:0x400
	ds_read_b64_tr_b16 v[148:149], v215 offset:0xc00
	s_nop 4
	v_fma_f32 v118, v64, s12, v160
	v_fma_f32 v119, v65, s12, v160
	v_fma_f32 v120, v66, s12, v160
	v_fma_f32 v121, v67, s12, v160
	v_fma_f32 v122, v68, s12, v160
	v_fma_f32 v123, v69, s12, v160
	s_waitcnt lgkmcnt(2)
	v_mfma_f32_32x32x16_bf16 v[16:31], v[130:133], v[142:145], v[16:31]
	ds_read_b64_tr_b16 v[142:143], v215 offset:0x1400
	ds_read_b64_tr_b16 v[144:145], v215 offset:0x1c00
	v_fma_f32 v124, v70, s12, v160
	v_fma_f32 v125, v71, s12, v160
	v_exp_f32_e32 v118, v118
	v_exp_f32_e32 v119, v119
	v_exp_f32_e32 v120, v120
	v_exp_f32_e32 v121, v121
	v_fma_f32 v244, v72, s12, v160
	v_fma_f32 v245, v73, s12, v160
	v_mfma_f32_32x32x16_bf16 v[16:31], v[162:165], v[134:137], v[16:31]
	ds_read_b64_tr_b16 v[138:139], v233 offset:0x2400
	ds_read_b64_tr_b16 v[140:141], v233 offset:0x2c00
	v_exp_f32_e32 v122, v122
	v_exp_f32_e32 v123, v123
	v_add_f32_e32 v208, v118, v208
	v_add_f32_e32 v208, v119, v208
	v_fma_f32 v246, v74, s12, v160
	v_fma_f32 v247, v75, s12, v160
	v_fma_f32 v76, v76, s12, v160
	v_fma_f32 v77, v77, s12, v160
	v_mfma_f32_32x32x16_bf16 v[16:31], v[166:169], v[126:129], v[16:31]
	ds_read_b64_tr_b16 v[64:65], v233 offset:0x3400
	ds_read_b64_tr_b16 v[66:67], v233 offset:0x3c00
	v_exp_f32_e32 v124, v124
	v_exp_f32_e32 v125, v125
	v_add_f32_e32 v208, v120, v208
	v_add_f32_e32 v208, v121, v208
	v_add_f32_e32 v208, v122, v208
	v_add_f32_e32 v208, v123, v208
	v_fma_f32 v78, v78, s12, v160
	v_fma_f32 v79, v79, s12, v160
	s_waitcnt lgkmcnt(6)
	v_mfma_f32_32x32x16_bf16 v[32:47], v[114:117], v[146:149], v[32:47]
	v_exp_f32_e32 v244, v244
	v_exp_f32_e32 v245, v245
	v_add_f32_e32 v208, v124, v208
	v_add_f32_e32 v208, v125, v208
	s_waitcnt lgkmcnt(4)
	v_mfma_f32_32x32x16_bf16 v[32:47], v[130:133], v[142:145], v[32:47]
	ds_read_b64_tr_b16 v[142:143], v215 offset:0x600
	ds_read_b64_tr_b16 v[144:145], v215 offset:0xe00
	ds_read_b64_tr_b16 v[126:127], v215 offset:0x1600
	ds_read_b64_tr_b16 v[128:129], v215 offset:0x1e00
	v_exp_f32_e32 v246, v246
	v_exp_f32_e32 v247, v247
	s_waitcnt lgkmcnt(6)
	v_mfma_f32_32x32x16_bf16 v[32:47], v[162:165], v[138:141], v[32:47]
	ds_read_b64_tr_b16 v[134:135], v233 offset:0x2600
	ds_read_b64_tr_b16 v[136:137], v233 offset:0x2e00
	v_exp_f32_e32 v76, v76
	v_exp_f32_e32 v77, v77
	v_add_f32_e32 v208, v244, v208
	v_add_f32_e32 v208, v245, v208
	s_waitcnt lgkmcnt(6)
	v_mfma_f32_32x32x16_bf16 v[32:47], v[166:169], v[64:67], v[32:47]
	ds_read_b64_tr_b16 v[68:69], v233 offset:0x3600
	ds_read_b64_tr_b16 v[70:71], v233 offset:0x3e00
	v_exp_f32_e32 v78, v78
	v_exp_f32_e32 v79, v79
	v_add_f32_e32 v208, v246, v208
	v_add_f32_e32 v208, v247, v208
	s_waitcnt lgkmcnt(6)
	v_mfma_f32_32x32x16_bf16 v[48:63], v[114:117], v[142:145], v[48:63]
	v_add_u32_e32 v64, s1, v210
	v_add_f32_e32 v208, v76, v208
	v_add_f32_e32 v208, v77, v208
	v_cvt_pk_bf16_f32 v114, v118, v119
	v_cvt_pk_bf16_f32 v115, v120, v121
	v_cvt_pk_bf16_f32 v116, v122, v123
	v_cvt_pk_bf16_f32 v117, v124, v125
	s_waitcnt lgkmcnt(4)
	v_mfma_f32_32x32x16_bf16 v[48:63], v[130:133], v[126:129], v[48:63]
	v_add_f32_e32 v208, v78, v208
	v_add_f32_e32 v208, v79, v208
	v_permlane32_swap_b32_e32 v114, v116
	v_permlane32_swap_b32_e32 v115, v117
	v_cvt_pk_bf16_f32 v130, v244, v245
	v_cvt_pk_bf16_f32 v131, v246, v247
	v_cvt_pk_bf16_f32 v132, v76, v77
	v_cvt_pk_bf16_f32 v133, v78, v79
	ds_write_b128 v64, v[114:117]
	s_waitcnt lgkmcnt(3)
	v_mfma_f32_32x32x16_bf16 v[48:63], v[162:165], v[134:137], v[48:63]
	v_permlane32_swap_b32_e32 v130, v132
	v_permlane32_swap_b32_e32 v131, v133
	ds_write_b128 v64, v[130:133] offset:16
	s_add_i32 s40, s40, 1
	s_add_i32 s0, s0, 64
	s_add_i32 s25, s25, 0x8000
	s_add_i32 s100, s0, -1
	s_cmp_ge_i32 s100, s33
	s_cselect_b32 s100, 1, 0
	s_sub_i32 s101, s0, 64
	s_cmp_le_i32 s101, s35
	s_cselect_b32 s101, 1, 0
	s_and_b32 s100, s100, s101
	s_cmp_eq_u32 s83, s40
	s_waitcnt vmcnt(0) lgkmcnt(0)
	s_barrier
	v_mfma_f32_32x32x16_bf16 v[48:63], v[166:169], v[68:71], v[48:63]
	s_cbranch_scc1 .LBB0_303
	s_cmp_lg_u32 s100, 0
	s_cbranch_scc1 .Lgen1
	s_branch .Lfast1
